# stage A QK/PV LDS pipelining, pipelined O read-modify-write with global loads
# baseline (speedup 1.0000x reference)
.LBB0_528:
	s_or_b64 exec, exec, s[0:1]
	global_load_dwordx2 v[2:3], v[146:147], off
	global_load_dwordx2 v[104:105], v[146:147], off offset:32
	global_load_dwordx2 v[106:107], v[146:147], off offset:64
	global_load_dwordx2 v[108:109], v[146:147], off offset:96
	global_load_dwordx2 v[110:111], v[146:147], off offset:128
	global_load_dwordx2 v[112:113], v[146:147], off offset:160
	global_load_dwordx2 v[114:115], v[146:147], off offset:192
	global_load_dwordx2 v[240:241], v[146:147], off offset:224
	v_pk_mul_f32 v[4:5], v[66:67], v[0:1] op_sel_hi:[1,0]
	v_pk_mul_f32 v[6:7], v[64:65], v[0:1] op_sel_hi:[1,0]
	s_waitcnt vmcnt(7)
	v_lshlrev_b32_e32 v1, 16, v2
	v_add_f32_e32 v1, v6, v1
	v_and_b32_e32 v2, 0xffff0000, v2
	v_lshlrev_b32_e32 v6, 16, v3
	v_and_b32_e32 v3, 0xffff0000, v3
	v_add_f32_e32 v2, v7, v2
	v_add_f32_e32 v3, v5, v3
	v_add_f32_e32 v4, v4, v6
	v_cvt_pk_bf16_f32 v2, v1, v2
	v_cvt_pk_bf16_f32 v3, v4, v3
	global_store_dwordx2 v[146:147], v[2:3], off
	v_pk_mul_f32 v[4:5], v[62:63], v[0:1] op_sel_hi:[1,0]
	v_pk_mul_f32 v[6:7], v[60:61], v[0:1] op_sel_hi:[1,0]
	s_waitcnt vmcnt(7)
	v_lshlrev_b32_e32 v1, 16, v104
	v_add_f32_e32 v1, v6, v1
	v_and_b32_e32 v2, 0xffff0000, v104
	v_lshlrev_b32_e32 v6, 16, v105
	v_and_b32_e32 v3, 0xffff0000, v105
	v_add_f32_e32 v2, v7, v2
	v_add_f32_e32 v3, v5, v3
	v_add_f32_e32 v4, v4, v6
	v_cvt_pk_bf16_f32 v2, v1, v2
	v_cvt_pk_bf16_f32 v3, v4, v3
	global_store_dwordx2 v[146:147], v[2:3], off offset:32
	v_pk_mul_f32 v[4:5], v[58:59], v[0:1] op_sel_hi:[1,0]
	v_pk_mul_f32 v[6:7], v[56:57], v[0:1] op_sel_hi:[1,0]
	s_waitcnt vmcnt(7)
	v_lshlrev_b32_e32 v1, 16, v106
	v_add_f32_e32 v1, v6, v1
	v_and_b32_e32 v2, 0xffff0000, v106
	v_lshlrev_b32_e32 v6, 16, v107
	v_and_b32_e32 v3, 0xffff0000, v107
	v_add_f32_e32 v2, v7, v2
	v_add_f32_e32 v3, v5, v3
	v_add_f32_e32 v4, v4, v6
	v_cvt_pk_bf16_f32 v2, v1, v2
	v_cvt_pk_bf16_f32 v3, v4, v3
	global_store_dwordx2 v[146:147], v[2:3], off offset:64
	v_pk_mul_f32 v[4:5], v[54:55], v[0:1] op_sel_hi:[1,0]
	v_pk_mul_f32 v[6:7], v[52:53], v[0:1] op_sel_hi:[1,0]
	s_waitcnt vmcnt(7)
	v_lshlrev_b32_e32 v1, 16, v108
	v_add_f32_e32 v1, v6, v1
	v_and_b32_e32 v2, 0xffff0000, v108
	v_lshlrev_b32_e32 v6, 16, v109
	v_and_b32_e32 v3, 0xffff0000, v109
	v_add_f32_e32 v2, v7, v2
	v_add_f32_e32 v3, v5, v3
	v_add_f32_e32 v4, v4, v6
	v_cvt_pk_bf16_f32 v2, v1, v2
	v_cvt_pk_bf16_f32 v3, v4, v3
	global_store_dwordx2 v[146:147], v[2:3], off offset:96
	v_pk_mul_f32 v[4:5], v[50:51], v[0:1] op_sel_hi:[1,0]
	v_pk_mul_f32 v[6:7], v[48:49], v[0:1] op_sel_hi:[1,0]
	s_waitcnt vmcnt(7)
	v_lshlrev_b32_e32 v1, 16, v110
	v_add_f32_e32 v1, v6, v1
	v_and_b32_e32 v2, 0xffff0000, v110
	v_lshlrev_b32_e32 v6, 16, v111
	v_and_b32_e32 v3, 0xffff0000, v111
	v_add_f32_e32 v2, v7, v2
	v_add_f32_e32 v3, v5, v3
	v_add_f32_e32 v4, v4, v6
	v_cvt_pk_bf16_f32 v2, v1, v2
	v_cvt_pk_bf16_f32 v3, v4, v3
	global_store_dwordx2 v[146:147], v[2:3], off offset:128
	v_pk_mul_f32 v[4:5], v[46:47], v[0:1] op_sel_hi:[1,0]
	v_pk_mul_f32 v[6:7], v[44:45], v[0:1] op_sel_hi:[1,0]
	s_waitcnt vmcnt(7)
	v_lshlrev_b32_e32 v1, 16, v112
	v_add_f32_e32 v1, v6, v1
	v_and_b32_e32 v2, 0xffff0000, v112
	v_lshlrev_b32_e32 v6, 16, v113
	v_and_b32_e32 v3, 0xffff0000, v113
	v_add_f32_e32 v2, v7, v2
	v_add_f32_e32 v3, v5, v3
	v_add_f32_e32 v4, v4, v6
	v_cvt_pk_bf16_f32 v2, v1, v2
	v_cvt_pk_bf16_f32 v3, v4, v3
	global_store_dwordx2 v[146:147], v[2:3], off offset:160
	v_pk_mul_f32 v[4:5], v[42:43], v[0:1] op_sel_hi:[1,0]
	v_pk_mul_f32 v[6:7], v[40:41], v[0:1] op_sel_hi:[1,0]
	s_waitcnt vmcnt(7)
	v_lshlrev_b32_e32 v1, 16, v114
	v_add_f32_e32 v1, v6, v1
	v_and_b32_e32 v2, 0xffff0000, v114
	v_lshlrev_b32_e32 v6, 16, v115
	v_and_b32_e32 v3, 0xffff0000, v115
	v_add_f32_e32 v2, v7, v2
	v_add_f32_e32 v3, v5, v3
	v_add_f32_e32 v4, v4, v6
	v_cvt_pk_bf16_f32 v2, v1, v2
	v_cvt_pk_bf16_f32 v3, v4, v3
	global_store_dwordx2 v[146:147], v[2:3], off offset:192
	v_pk_mul_f32 v[4:5], v[38:39], v[0:1] op_sel_hi:[1,0]
	v_pk_mul_f32 v[0:1], v[36:37], v[0:1] op_sel_hi:[1,0]
	s_waitcnt vmcnt(7)
	v_lshlrev_b32_e32 v6, 16, v240
	v_and_b32_e32 v2, 0xffff0000, v240
	v_add_f32_e32 v0, v0, v6
	v_add_f32_e32 v1, v1, v2
	v_lshlrev_b32_e32 v2, 16, v241
	v_and_b32_e32 v3, 0xffff0000, v241
	v_add_f32_e32 v2, v4, v2
	v_add_f32_e32 v3, v5, v3
	v_cvt_pk_bf16_f32 v0, v0, v1
	v_cvt_pk_bf16_f32 v1, v2, v3
	global_store_dwordx2 v[146:147], v[0:1], off offset:224
	s_add_i32 s66, s66, s6
	s_cmpk_gt_i32 s66, 0x1ff
	s_cbranch_scc1 .LBB0_717

.LBB0_550:
	s_lshl_b32 s2, s21, 10
	s_sub_i32 s16, s7, s2
	s_cmpk_lt_i32 s16, 0x80
	s_cselect_b64 s[2:3], -1, 0
	s_cmpk_gt_i32 s16, 0x7f
	s_setprio 1
	ds_read_b128 v[50:53], v66
	ds_read_b128 v[240:243], v66 offset:64
	ds_read_b128 v[248:251], v66 offset:128
	ds_read_b128 v[252:255], v66 offset:192
	s_waitcnt lgkmcnt(3)
	v_mfma_f32_16x16x32_bf16 v[8:11], v[50:53], v[20:23], 0
	ds_read_b128 v[50:53], v66 offset:4352
	s_waitcnt lgkmcnt(3)
	v_mfma_f32_16x16x32_bf16 v[8:11], v[240:243], v[24:27], v[8:11]
	ds_read_b128 v[240:243], v66 offset:4416
	s_waitcnt lgkmcnt(3)
	v_mfma_f32_16x16x32_bf16 v[8:11], v[248:251], v[30:33], v[8:11]
	ds_read_b128 v[248:251], v66 offset:4480
	s_waitcnt lgkmcnt(3)
	v_mfma_f32_16x16x32_bf16 v[8:11], v[252:255], v[34:37], v[8:11]
	ds_read_b128 v[252:255], v66 offset:4544
	s_waitcnt lgkmcnt(3)
	v_mfma_f32_16x16x32_bf16 v[12:15], v[50:53], v[20:23], 0
	ds_read_b128 v[50:53], v66 offset:8704
	s_waitcnt lgkmcnt(3)
	v_mfma_f32_16x16x32_bf16 v[12:15], v[240:243], v[24:27], v[12:15]
	ds_read_b128 v[240:243], v66 offset:8768
	s_waitcnt lgkmcnt(3)
	v_mfma_f32_16x16x32_bf16 v[12:15], v[248:251], v[30:33], v[12:15]
	ds_read_b128 v[248:251], v66 offset:8832
	s_waitcnt lgkmcnt(3)
	v_mfma_f32_16x16x32_bf16 v[12:15], v[252:255], v[34:37], v[12:15]
	ds_read_b128 v[252:255], v66 offset:8896
	s_waitcnt lgkmcnt(3)
	v_mfma_f32_16x16x32_bf16 v[38:41], v[50:53], v[20:23], 0
	ds_read_b128 v[50:53], v66 offset:13056
	s_waitcnt lgkmcnt(3)
	v_mfma_f32_16x16x32_bf16 v[38:41], v[240:243], v[24:27], v[38:41]
	ds_read_b128 v[240:243], v66 offset:13120
	s_waitcnt lgkmcnt(3)
	v_mfma_f32_16x16x32_bf16 v[38:41], v[248:251], v[30:33], v[38:41]
	ds_read_b128 v[248:251], v66 offset:13184
	s_waitcnt lgkmcnt(3)
	v_mfma_f32_16x16x32_bf16 v[38:41], v[252:255], v[34:37], v[38:41]
	ds_read_b128 v[252:255], v66 offset:13248
	s_waitcnt lgkmcnt(3)
	v_mfma_f32_16x16x32_bf16 v[42:45], v[50:53], v[20:23], 0
	s_waitcnt lgkmcnt(2)
	v_mfma_f32_16x16x32_bf16 v[42:45], v[240:243], v[24:27], v[42:45]
	s_waitcnt lgkmcnt(1)
	v_mfma_f32_16x16x32_bf16 v[42:45], v[248:251], v[30:33], v[42:45]
	s_waitcnt lgkmcnt(0)
	v_mfma_f32_16x16x32_bf16 v[42:45], v[252:255], v[34:37], v[42:45]
	s_setprio 0
	s_mov_b64 s[16:17], -1
	s_cbranch_scc1 .LBB0_552
	v_lshl_add_u32 v50, s21, 6, v49
	v_lshlrev_b32_e32 v51, 4, v50
	v_not_b32_e32 v50, v50
	v_sub_u32_e32 v60, v84, v51
	v_sub_u32_e32 v57, v48, v51
	v_add_u32_e32 v61, 0xffffffc1, v60
	v_lshl_add_u32 v63, v50, 4, v48
	v_add_u32_e32 v69, 0xfffffee1, v60
	v_add_u32_e32 v70, 0xffffffb1, v60
	v_add_u32_e32 v71, 0xfffffec1, v60
	v_add_u32_e32 v72, 0xfffffed1, v60
	v_add_u32_e32 v74, 0xfffffeb1, v60
	v_med3_i32 v52, v57, 0, v207
	v_med3_i32 v50, v63, 0, v207
	v_med3_i32 v51, v61, 0, v207
	v_med3_i32 v53, v70, 0, v207
	v_med3_i32 v54, v69, 0, v207
	v_med3_i32 v55, v72, 0, v207
	v_med3_i32 v56, v71, 0, v207
	v_med3_i32 v58, v74, 0, v207
	v_lshl_add_u32 v52, v52, 2, v151
	v_lshl_add_u32 v50, v50, 2, v151
	v_lshl_add_u32 v51, v51, 2, v151
	v_lshl_add_u32 v53, v53, 2, v151
	v_lshl_add_u32 v54, v54, 2, v151
	v_lshl_add_u32 v55, v55, 2, v151
	v_lshl_add_u32 v56, v56, 2, v151
	v_lshl_add_u32 v58, v58, 2, v151
	ds_read_b32 v59, v52 offset:9216
	ds_read_b32 v50, v50 offset:9216
	ds_read_b32 v51, v51 offset:9216
	ds_read_b32 v52, v53 offset:9216
	ds_read_b32 v53, v54 offset:9216
	ds_read_b32 v54, v55 offset:9216
	ds_read_b32 v55, v56 offset:9216
	ds_read_b32 v56, v58 offset:9216
	s_waitcnt lgkmcnt(7)
	v_add_f32_e32 v58, v8, v59
	v_cmp_lt_i32_e32 vcc, -1, v57
	v_mov_b32_e32 v59, v10
	v_add_u32_e32 v77, 0xfffffdb1, v60
	v_cndmask_b32_e32 v64, v208, v58, vcc
	v_mov_b32_e32 v58, v9
	s_waitcnt lgkmcnt(5)
	v_pk_add_f32 v[50:51], v[58:59], v[50:51]
	v_cmp_lt_i32_e32 vcc, -1, v61
	v_add_u32_e32 v76, 0xfffffce1, v60
	v_add_u32_e32 v79, 0xfffffcd1, v60
	v_cndmask_b32_e32 v62, v208, v51, vcc
	v_cmp_lt_i32_e32 vcc, -1, v63
	v_add_u32_e32 v75, 0xfffffdd1, v60
	v_add_u32_e32 v78, 0xfffffcc1, v60
	v_cndmask_b32_e32 v65, v208, v50, vcc
	v_pk_mov_b32 v[50:51], v[10:11], v[12:13] op_sel:[1,0]
	v_cmp_lt_i32_e32 vcc, -1, v69
	s_waitcnt lgkmcnt(3)
	v_pk_add_f32 v[50:51], v[50:51], v[52:53]
	v_max3_f32 v57, v64, s82, v65
	v_cndmask_b32_e32 v58, v208, v51, vcc
	v_cmp_lt_i32_e32 vcc, -1, v70
	v_add_u32_e32 v69, 0xfffffdc1, v60
	v_mov_b32_e32 v51, v14
	v_cndmask_b32_e32 v63, v208, v50, vcc
	v_max3_f32 v52, v57, v62, v63
	v_med3_i32 v57, v69, 0, v207
	v_mov_b32_e32 v50, v13
	v_lshl_add_u32 v70, v57, 2, v151
	v_med3_i32 v57, v77, 0, v207
	s_waitcnt lgkmcnt(1)
	v_pk_add_f32 v[50:51], v[50:51], v[54:55]
	v_cmp_lt_i32_e32 vcc, -1, v71
	v_lshl_add_u32 v71, v57, 2, v151
	v_med3_i32 v57, v76, 0, v207
	v_cndmask_b32_e32 v54, v208, v51, vcc
	v_cmp_lt_i32_e32 vcc, -1, v72
	v_add_u32_e32 v55, 0xfffffde1, v60
	v_lshl_add_u32 v72, v57, 2, v151
	v_med3_i32 v57, v79, 0, v207
	v_cndmask_b32_e32 v59, v208, v50, vcc
	v_med3_i32 v50, v55, 0, v207
	v_med3_i32 v53, v75, 0, v207
	v_lshl_add_u32 v73, v57, 2, v151
	v_med3_i32 v57, v78, 0, v207
	v_add_u32_e32 v81, 0xfffffcb1, v60
	v_max3_f32 v61, v52, v58, v59
	v_lshl_add_u32 v52, v50, 2, v151
	v_pk_mov_b32 v[50:51], v[14:15], v[38:39] op_sel:[1,0]
	v_lshl_add_u32 v53, v53, 2, v151
	v_lshl_add_u32 v80, v57, 2, v151
	v_med3_i32 v57, v81, 0, v207
	v_lshl_add_u32 v60, v57, 2, v151
	ds_read_b32 v57, v52 offset:9216
	ds_read_b32 v52, v53 offset:9216
	ds_read_b32 v53, v70 offset:9216
	ds_read_b32 v70, v71 offset:9216
	ds_read_b32 v71, v72 offset:9216
	ds_read_b32 v72, v73 offset:9216
	ds_read_b32 v73, v80 offset:9216
	ds_read_b32 v80, v60 offset:9216
	s_waitcnt lgkmcnt(7)
	v_pk_add_f32 v[50:51], v[50:51], v[56:57]
	v_cmp_lt_i32_e32 vcc, -1, v55
	s_mov_b64 s[16:17], 0
	s_nop 0
	v_cndmask_b32_e32 v60, v208, v51, vcc
	v_cmp_lt_i32_e32 vcc, -1, v74
	v_mov_b32_e32 v51, v40
	s_nop 0
	v_cndmask_b32_e32 v55, v208, v50, vcc
	v_mov_b32_e32 v50, v39
	s_waitcnt lgkmcnt(5)
	v_pk_add_f32 v[50:51], v[50:51], v[52:53]
	v_cmp_lt_i32_e32 vcc, -1, v69
	v_max3_f32 v57, v61, v54, v55
	s_nop 0
	v_cndmask_b32_e32 v56, v208, v51, vcc
	v_cmp_lt_i32_e32 vcc, -1, v75
	s_nop 1
	v_cndmask_b32_e32 v61, v208, v50, vcc
	v_pk_mov_b32 v[50:51], v[40:41], v[42:43] op_sel:[1,0]
	v_cmp_lt_i32_e32 vcc, -1, v76
	s_waitcnt lgkmcnt(3)
	v_pk_add_f32 v[50:51], v[50:51], v[70:71]
	v_max3_f32 v53, v57, v60, v61
	v_cndmask_b32_e32 v52, v208, v51, vcc
	v_cmp_lt_i32_e32 vcc, -1, v77
	v_mov_b32_e32 v51, v44
	s_nop 0
	v_cndmask_b32_e32 v57, v208, v50, vcc
	v_mov_b32_e32 v50, v43
	s_waitcnt lgkmcnt(1)
	v_pk_add_f32 v[70:71], v[50:51], v[72:73]
	v_cmp_lt_i32_e32 vcc, -1, v78
	v_max3_f32 v69, v53, v56, v57
	s_waitcnt lgkmcnt(0)
	v_add_f32_e32 v51, v45, v80
	v_cndmask_b32_e32 v50, v208, v71, vcc
	v_cmp_lt_i32_e32 vcc, -1, v79
	s_nop 1
	v_cndmask_b32_e32 v53, v208, v70, vcc
	v_cmp_lt_i32_e32 vcc, -1, v81
	v_max3_f32 v69, v69, v52, v53
	s_nop 0
	v_cndmask_b32_e32 v51, v208, v51, vcc
	v_max3_f32 v69, v69, v50, v51

.LBB0_569:
	s_lshl_b32 s2, s16, 10
	s_sub_i32 s12, s7, s2
	s_cmpk_lt_i32 s12, 0x80
	s_cselect_b64 s[2:3], -1, 0
	s_cmpk_gt_i32 s12, 0x7f
	s_setprio 1
	ds_read_b128 v[112:115], v173
	ds_read_b128 v[240:243], v173 offset:64
	ds_read_b128 v[248:251], v173 offset:128
	ds_read_b128 v[252:255], v173 offset:192
	s_waitcnt lgkmcnt(3)
	v_mfma_f32_16x16x32_bf16 v[0:3], v[112:115], v[20:23], 0
	ds_read_b128 v[112:115], v173 offset:4352
	s_waitcnt lgkmcnt(3)
	v_mfma_f32_16x16x32_bf16 v[0:3], v[240:243], v[24:27], v[0:3]
	ds_read_b128 v[240:243], v173 offset:4416
	s_waitcnt lgkmcnt(3)
	v_mfma_f32_16x16x32_bf16 v[0:3], v[248:251], v[30:33], v[0:3]
	ds_read_b128 v[248:251], v173 offset:4480
	s_waitcnt lgkmcnt(3)
	v_mfma_f32_16x16x32_bf16 v[0:3], v[252:255], v[34:37], v[0:3]
	ds_read_b128 v[252:255], v173 offset:4544
	s_waitcnt lgkmcnt(3)
	v_mfma_f32_16x16x32_bf16 v[4:7], v[112:115], v[20:23], 0
	ds_read_b128 v[112:115], v173 offset:8704
	s_waitcnt lgkmcnt(3)
	v_mfma_f32_16x16x32_bf16 v[4:7], v[240:243], v[24:27], v[4:7]
	ds_read_b128 v[240:243], v173 offset:8768
	s_waitcnt lgkmcnt(3)
	v_mfma_f32_16x16x32_bf16 v[4:7], v[248:251], v[30:33], v[4:7]
	ds_read_b128 v[248:251], v173 offset:8832
	s_waitcnt lgkmcnt(3)
	v_mfma_f32_16x16x32_bf16 v[4:7], v[252:255], v[34:37], v[4:7]
	ds_read_b128 v[252:255], v173 offset:8896
	s_waitcnt lgkmcnt(3)
	v_mfma_f32_16x16x32_bf16 v[8:11], v[112:115], v[20:23], 0
	ds_read_b128 v[112:115], v173 offset:13056
	s_waitcnt lgkmcnt(3)
	v_mfma_f32_16x16x32_bf16 v[8:11], v[240:243], v[24:27], v[8:11]
	ds_read_b128 v[240:243], v173 offset:13120
	s_waitcnt lgkmcnt(3)
	v_mfma_f32_16x16x32_bf16 v[8:11], v[248:251], v[30:33], v[8:11]
	ds_read_b128 v[248:251], v173 offset:13184
	s_waitcnt lgkmcnt(3)
	v_mfma_f32_16x16x32_bf16 v[8:11], v[252:255], v[34:37], v[8:11]
	ds_read_b128 v[252:255], v173 offset:13248
	s_waitcnt lgkmcnt(3)
	v_mfma_f32_16x16x32_bf16 v[12:15], v[112:115], v[20:23], 0
	s_waitcnt lgkmcnt(2)
	v_mfma_f32_16x16x32_bf16 v[12:15], v[240:243], v[24:27], v[12:15]
	s_waitcnt lgkmcnt(1)
	v_mfma_f32_16x16x32_bf16 v[12:15], v[248:251], v[30:33], v[12:15]
	s_waitcnt lgkmcnt(0)
	v_mfma_f32_16x16x32_bf16 v[12:15], v[252:255], v[34:37], v[12:15]
	s_setprio 0
	s_mov_b64 s[12:13], -1
	s_cbranch_scc1 .LBB0_571
	s_lshl_b32 s12, s16, 6
	v_subrev_u32_e32 v112, s12, v171
	v_xad_u32 v113, s12, -1, v171
	v_subrev_u32_e32 v114, s12, v98
	v_subrev_u32_e32 v115, s12, v29
	v_subrev_u32_e32 v116, s12, v100
	v_subrev_u32_e32 v117, s12, v85
	v_subrev_u32_e32 v124, s12, v102
	v_lshl_add_u32 v118, v112, 4, v96
	v_lshl_add_u32 v119, v113, 4, v96
	v_lshl_add_u32 v120, v115, 4, v107
	v_lshl_add_u32 v121, v114, 4, v96
	v_lshl_add_u32 v122, v117, 4, v107
	v_lshl_add_u32 v123, v116, 4, v96
	v_subrev_u32_e32 v125, s12, v97
	v_lshl_add_u32 v176, v124, 4, v96
	v_med3_i32 v112, v118, 0, v207
	v_med3_i32 v113, v119, 0, v207
	v_med3_i32 v114, v121, 0, v207
	v_med3_i32 v115, v120, 0, v207
	v_med3_i32 v116, v123, 0, v207
	v_med3_i32 v117, v122, 0, v207
	v_lshl_add_u32 v175, v125, 4, v107
	v_med3_i32 v124, v176, 0, v207
	v_lshl_add_u32 v112, v112, 2, v151
	v_lshl_add_u32 v113, v113, 2, v151
	v_lshl_add_u32 v114, v114, 2, v151
	v_lshl_add_u32 v115, v115, 2, v151
	v_lshl_add_u32 v116, v116, 2, v151
	v_lshl_add_u32 v117, v117, 2, v151
	v_lshl_add_u32 v124, v124, 2, v151
	v_med3_i32 v125, v175, 0, v207
	v_lshl_add_u32 v125, v125, 2, v151
	ds_read_b32 v126, v112 offset:9216
	ds_read_b32 v127, v113 offset:9216
	ds_read_b32 v112, v114 offset:9216
	ds_read_b32 v113, v115 offset:9216
	ds_read_b32 v114, v116 offset:9216
	ds_read_b32 v115, v117 offset:9216
	ds_read_b32 v116, v124 offset:9216
	ds_read_b32 v117, v125 offset:9216
	s_waitcnt lgkmcnt(7)
	v_add_f32_e32 v124, v0, v126
	v_cmp_lt_i32_e32 vcc, -1, v118
	s_waitcnt lgkmcnt(6)
	v_add_f32_e32 v118, v1, v127
	s_waitcnt lgkmcnt(4)
	v_pk_add_f32 v[112:113], v[2:3], v[112:113]
	v_cndmask_b32_e32 v126, v208, v124, vcc
	v_cmp_lt_i32_e32 vcc, -1, v119
	v_subrev_u32_e32 v177, s12, v105
	v_lshl_add_u32 v183, v177, 4, v107
	v_cndmask_b32_e32 v127, v208, v118, vcc
	v_cmp_lt_i32_e32 vcc, -1, v121
	s_nop 1
	v_cndmask_b32_e32 v124, v208, v112, vcc
	v_cmp_lt_i32_e32 vcc, -1, v120
	s_nop 1
	v_cndmask_b32_e32 v125, v208, v113, vcc
	s_waitcnt lgkmcnt(2)
	v_pk_add_f32 v[112:113], v[4:5], v[114:115]
	v_cmp_lt_i32_e32 vcc, -1, v123
	v_subrev_u32_e32 v114, s12, v106
	v_subrev_u32_e32 v115, s12, v101
	v_cndmask_b32_e32 v120, v208, v112, vcc
	v_cmp_lt_i32_e32 vcc, -1, v122
	v_lshl_add_u32 v180, v114, 4, v96
	v_subrev_u32_e32 v122, s12, v108
	v_cndmask_b32_e32 v121, v208, v113, vcc
	s_waitcnt lgkmcnt(0)
	v_pk_add_f32 v[112:113], v[6:7], v[116:117]
	v_cmp_lt_i32_e32 vcc, -1, v176
	v_subrev_u32_e32 v176, s12, v110
	v_lshl_add_u32 v184, v176, 4, v96
	v_cndmask_b32_e32 v118, v208, v112, vcc
	v_cmp_lt_i32_e32 vcc, -1, v175
	v_subrev_u32_e32 v112, s12, v104
	v_lshl_add_u32 v117, v112, 4, v96
	v_cndmask_b32_e32 v119, v208, v113, vcc
	v_subrev_u32_e32 v113, s12, v99
	v_lshl_add_u32 v116, v113, 4, v107
	v_lshl_add_u32 v175, v115, 4, v107
	v_subrev_u32_e32 v123, s12, v103
	v_med3_i32 v176, v184, 0, v207
	v_med3_i32 v112, v117, 0, v207
	v_med3_i32 v113, v116, 0, v207
	v_med3_i32 v114, v180, 0, v207
	v_med3_i32 v115, v175, 0, v207
	v_lshl_add_u32 v181, v123, 4, v107
	v_lshl_add_u32 v182, v122, 4, v96
	v_lshl_add_u32 v178, v176, 2, v151
	v_med3_i32 v176, v183, 0, v207
	v_lshl_add_u32 v112, v112, 2, v151
	v_lshl_add_u32 v113, v113, 2, v151
	v_lshl_add_u32 v114, v114, 2, v151
	v_lshl_add_u32 v115, v115, 2, v151
	v_med3_i32 v122, v182, 0, v207
	v_med3_i32 v123, v181, 0, v207
	v_lshl_add_u32 v179, v176, 2, v151
	v_lshl_add_u32 v122, v122, 2, v151
	v_lshl_add_u32 v123, v123, 2, v151
	ds_read_b32 v112, v112 offset:9216
	ds_read_b32 v113, v113 offset:9216
	ds_read_b32 v114, v114 offset:9216
	ds_read_b32 v115, v115 offset:9216
	ds_read_b32 v176, v122 offset:9216
	ds_read_b32 v177, v123 offset:9216
	ds_read_b32 v178, v178 offset:9216
	ds_read_b32 v179, v179 offset:9216
	s_waitcnt lgkmcnt(6)
	v_pk_add_f32 v[112:113], v[8:9], v[112:113]
	v_cmp_lt_i32_e32 vcc, -1, v117
	s_mov_b64 s[12:13], 0
	s_nop 0
	v_cndmask_b32_e32 v122, v208, v112, vcc
	v_cmp_lt_i32_e32 vcc, -1, v116
	s_nop 1
	v_cndmask_b32_e32 v123, v208, v113, vcc
	s_waitcnt lgkmcnt(4)
	v_pk_add_f32 v[112:113], v[10:11], v[114:115]
	v_cmp_lt_i32_e32 vcc, -1, v180
	s_nop 1
	v_cndmask_b32_e32 v116, v208, v112, vcc
	v_cmp_lt_i32_e32 vcc, -1, v175
	s_nop 1
	v_cndmask_b32_e32 v117, v208, v113, vcc
	s_waitcnt lgkmcnt(2)
	v_pk_add_f32 v[112:113], v[12:13], v[176:177]
	v_cmp_lt_i32_e32 vcc, -1, v182
	s_nop 1
	v_cndmask_b32_e32 v114, v208, v112, vcc
	v_cmp_lt_i32_e32 vcc, -1, v181
	s_nop 1
	v_cndmask_b32_e32 v115, v208, v113, vcc
	s_waitcnt lgkmcnt(0)
	v_pk_add_f32 v[112:113], v[14:15], v[178:179]
	v_cmp_lt_i32_e32 vcc, -1, v184
	s_nop 1
	v_cndmask_b32_e32 v112, v208, v112, vcc
	v_cmp_lt_i32_e32 vcc, -1, v183
	s_nop 1
	v_cndmask_b32_e32 v113, v208, v113, vcc

.LBB0_577:
	v_lshl_add_u32 v112, s16, 6, v172
	ds_read_b32 v114, v112 offset:11328
	v_add_f32_e32 v113, v0, v1
	v_add_f32_e32 v113, v2, v113
	v_add_f32_e32 v113, v3, v113
	s_waitcnt lgkmcnt(0)
	v_fmac_f32_e32 v114, v166, v113
	ds_write_b32 v112, v114 offset:11328
	ds_read_b32 v114, v112 offset:11344
	v_add_f32_e32 v113, v4, v5
	v_add_f32_e32 v113, v6, v113
	v_add_f32_e32 v113, v7, v113
	s_waitcnt lgkmcnt(0)
	v_fmac_f32_e32 v114, v166, v113
	ds_write_b32 v112, v114 offset:11344
	ds_read_b32 v114, v112 offset:11360
	v_add_f32_e32 v113, v8, v9
	v_add_f32_e32 v113, v10, v113
	v_add_f32_e32 v113, v11, v113
	s_waitcnt lgkmcnt(0)
	v_fmac_f32_e32 v114, v166, v113
	ds_write_b32 v112, v114 offset:11360
	ds_read_b32 v114, v112 offset:11376
	v_add_f32_e32 v113, v12, v13
	v_add_f32_e32 v113, v14, v113
	v_add_f32_e32 v113, v15, v113
	s_waitcnt lgkmcnt(0)
	v_fmac_f32_e32 v114, v166, v113
	ds_write_b32 v112, v114 offset:11376
	ds_read_b32 v113, v112 offset:11332
	s_waitcnt lgkmcnt(0)
	v_fmac_f32_e32 v113, v166, v3
	ds_write_b32 v112, v113 offset:11332
	ds_read_b32 v113, v112 offset:11348
	s_waitcnt lgkmcnt(0)
	v_fmac_f32_e32 v113, v166, v7
	ds_write_b32 v112, v113 offset:11348
	ds_read_b32 v113, v112 offset:11364
	s_waitcnt lgkmcnt(0)
	v_fmac_f32_e32 v113, v166, v11
	ds_write_b32 v112, v113 offset:11364
	ds_read_b32 v113, v112 offset:11380
	s_waitcnt lgkmcnt(0)
	v_fmac_f32_e32 v113, v166, v15
	ds_write_b32 v112, v113 offset:11380
	s_setprio 1
	v_cvt_pk_bf16_f32 v0, v0, v1
	v_cvt_pk_bf16_f32 v1, v2, v3
	v_cvt_pk_bf16_f32 v2, v4, v5
	v_cvt_pk_bf16_f32 v3, v6, v7
	v_add_u32_e32 v112, 0x800, v174
	v_add_u32_e32 v113, 0x1000, v174
	v_add_u32_e32 v114, 0x1800, v174
	v_add_u32_e32 v115, 0x2000, v174
	v_add_u32_e32 v116, 0x2800, v174
	v_add_u32_e32 v117, 0x3000, v174
	v_add_u32_e32 v118, 0x3800, v174
	ds_read2_b64 v[240:243], v174 offset1:4
	ds_read2_b64 v[248:251], v112 offset0:32 offset1:36
	ds_read2_b64 v[252:255], v113 offset0:64 offset1:68
	s_waitcnt lgkmcnt(2)
	v_mfma_f32_16x16x32_bf16 v[4:7], v[240:243], v[0:3], v[16:19]
	ds_read2_b64 v[240:243], v114 offset0:96 offset1:100
	s_waitcnt lgkmcnt(2)
	v_mfma_f32_16x16x32_bf16 v[38:41], v[248:251], v[0:3], v[38:41]
	ds_read2_b64 v[248:251], v115 offset0:128 offset1:132
	s_waitcnt lgkmcnt(2)
	v_mfma_f32_16x16x32_bf16 v[42:45], v[252:255], v[0:3], v[42:45]
	ds_read2_b64 v[252:255], v116 offset0:160 offset1:164
	s_waitcnt lgkmcnt(2)
	v_mfma_f32_16x16x32_bf16 v[46:49], v[240:243], v[0:3], v[46:49]
	ds_read2_b64 v[240:243], v117 offset0:192 offset1:196
	s_waitcnt lgkmcnt(2)
	v_mfma_f32_16x16x32_bf16 v[50:53], v[248:251], v[0:3], v[50:53]
	ds_read2_b64 v[248:251], v118 offset0:224 offset1:228
	s_waitcnt lgkmcnt(2)
	v_mfma_f32_16x16x32_bf16 v[54:57], v[252:255], v[0:3], v[54:57]
	ds_read2_b64 v[252:255], v174 offset0:8 offset1:12
	s_waitcnt lgkmcnt(2)
	v_mfma_f32_16x16x32_bf16 v[58:61], v[240:243], v[0:3], v[58:61]
	ds_read2_b64 v[240:243], v112 offset0:40 offset1:44
	s_waitcnt lgkmcnt(2)
	v_mfma_f32_16x16x32_bf16 v[0:3], v[248:251], v[0:3], v[62:65]
	ds_read2_b64 v[248:251], v113 offset0:72 offset1:76
	v_cvt_pk_bf16_f32 v8, v8, v9
	v_cvt_pk_bf16_f32 v9, v10, v11
	v_cvt_pk_bf16_f32 v10, v12, v13
	v_cvt_pk_bf16_f32 v11, v14, v15
	s_nop 1
	s_waitcnt lgkmcnt(2)
	v_mfma_f32_16x16x32_bf16 v[16:19], v[252:255], v[8:11], v[4:7]
	ds_read2_b64 v[252:255], v114 offset0:104 offset1:108
	s_waitcnt lgkmcnt(2)
	v_mfma_f32_16x16x32_bf16 v[38:41], v[240:243], v[8:11], v[38:41]
	ds_read2_b64 v[240:243], v115 offset0:136 offset1:140
	s_waitcnt lgkmcnt(2)
	v_mfma_f32_16x16x32_bf16 v[42:45], v[248:251], v[8:11], v[42:45]
	ds_read2_b64 v[248:251], v116 offset0:168 offset1:172
	s_waitcnt lgkmcnt(2)
	v_mfma_f32_16x16x32_bf16 v[46:49], v[252:255], v[8:11], v[46:49]
	ds_read2_b64 v[252:255], v117 offset0:200 offset1:204
	s_waitcnt lgkmcnt(2)
	v_mfma_f32_16x16x32_bf16 v[50:53], v[240:243], v[8:11], v[50:53]
	ds_read2_b64 v[240:243], v118 offset0:232 offset1:236
	s_waitcnt lgkmcnt(2)
	v_mfma_f32_16x16x32_bf16 v[54:57], v[248:251], v[8:11], v[54:57]
	s_waitcnt lgkmcnt(1)
	v_mfma_f32_16x16x32_bf16 v[58:61], v[252:255], v[8:11], v[58:61]
	s_waitcnt lgkmcnt(0)
	v_mfma_f32_16x16x32_bf16 v[62:65], v[240:243], v[8:11], v[0:3]
	s_setprio 0
	s_andn2_b64 vcc, exec, s[0:1]
	s_barrier
	s_cbranch_vccnz .LBB0_566
	s_waitcnt vmcnt(3)
	ds_write_b128 v167, v[70:73]
	s_waitcnt vmcnt(2)
	ds_write_b128 v168, v[74:77]
	s_waitcnt vmcnt(1)
	ds_write_b128 v169, v[78:81]
	s_waitcnt vmcnt(0)
	ds_write_b128 v170, v[66:69]
	s_branch .LBB0_566

.LBB0_683:
	s_or_b64 exec, exec, s[0:1]
	v_lshl_add_u64 v[144:145], v[158:159], 0, v[164:165]
	global_load_dwordx2 v[102:103], v[144:145], off
	global_load_dwordx2 v[104:105], v[144:145], off offset:32
	global_load_dwordx2 v[106:107], v[144:145], off offset:64
	global_load_dwordx2 v[108:109], v[144:145], off offset:96
	global_load_dwordx2 v[110:111], v[144:145], off offset:128
	global_load_dwordx2 v[112:113], v[144:145], off offset:160
	global_load_dwordx2 v[114:115], v[144:145], off offset:192
	global_load_dwordx2 v[240:241], v[144:145], off offset:224
	v_pk_mul_f32 v[96:97], v[96:97], v[100:101] op_sel_hi:[1,0]
	v_pk_mul_f32 v[98:99], v[98:99], v[100:101] op_sel_hi:[1,0]
	v_pk_mul_f32 v[92:93], v[92:93], v[100:101] op_sel_hi:[1,0]
	v_pk_mul_f32 v[94:95], v[94:95], v[100:101] op_sel_hi:[1,0]
	v_pk_mul_f32 v[88:89], v[88:89], v[100:101] op_sel_hi:[1,0]
	v_pk_mul_f32 v[90:91], v[90:91], v[100:101] op_sel_hi:[1,0]
	v_pk_mul_f32 v[84:85], v[84:85], v[100:101] op_sel_hi:[1,0]
	v_pk_mul_f32 v[86:87], v[86:87], v[100:101] op_sel_hi:[1,0]
	v_pk_mul_f32 v[80:81], v[80:81], v[100:101] op_sel_hi:[1,0]
	v_pk_mul_f32 v[82:83], v[82:83], v[100:101] op_sel_hi:[1,0]
	v_pk_mul_f32 v[76:77], v[76:77], v[100:101] op_sel_hi:[1,0]
	v_pk_mul_f32 v[78:79], v[78:79], v[100:101] op_sel_hi:[1,0]
	v_pk_mul_f32 v[72:73], v[72:73], v[100:101] op_sel_hi:[1,0]
	v_pk_mul_f32 v[74:75], v[74:75], v[100:101] op_sel_hi:[1,0]
	v_pk_mul_f32 v[68:69], v[68:69], v[100:101] op_sel_hi:[1,0]
	v_pk_mul_f32 v[70:71], v[70:71], v[100:101] op_sel_hi:[1,0]
	s_waitcnt vmcnt(7)
	v_lshlrev_b32_e32 v29, 16, v102
	v_add_f32_e32 v29, v96, v29
	v_and_b32_e32 v31, 0xffff0000, v102
	v_lshlrev_b32_e32 v96, 16, v103
	v_add_f32_e32 v31, v97, v31
	v_add_f32_e32 v97, v98, v96
	v_and_b32_e32 v96, 0xffff0000, v103
	v_add_f32_e32 v98, v99, v96
	v_cvt_pk_bf16_f32 v96, v29, v31
	v_cvt_pk_bf16_f32 v97, v97, v98
	global_store_dwordx2 v[144:145], v[96:97], off
	s_waitcnt vmcnt(7)
	v_lshlrev_b32_e32 v29, 16, v104
	v_add_f32_e32 v29, v92, v29
	v_and_b32_e32 v31, 0xffff0000, v104
	v_lshlrev_b32_e32 v92, 16, v105
	v_add_f32_e32 v31, v93, v31
	v_add_f32_e32 v93, v94, v92
	v_and_b32_e32 v92, 0xffff0000, v105
	v_add_f32_e32 v94, v95, v92
	v_cvt_pk_bf16_f32 v92, v29, v31
	v_cvt_pk_bf16_f32 v93, v93, v94
	global_store_dwordx2 v[144:145], v[92:93], off offset:32
	s_waitcnt vmcnt(7)
	v_lshlrev_b32_e32 v29, 16, v106
	v_add_f32_e32 v29, v88, v29
	v_and_b32_e32 v31, 0xffff0000, v106
	v_lshlrev_b32_e32 v88, 16, v107
	v_add_f32_e32 v31, v89, v31
	v_add_f32_e32 v89, v90, v88
	v_and_b32_e32 v88, 0xffff0000, v107
	v_add_f32_e32 v90, v91, v88
	v_cvt_pk_bf16_f32 v88, v29, v31
	v_cvt_pk_bf16_f32 v89, v89, v90
	global_store_dwordx2 v[144:145], v[88:89], off offset:64
	s_waitcnt vmcnt(7)
	v_lshlrev_b32_e32 v29, 16, v108
	v_add_f32_e32 v29, v84, v29
	v_and_b32_e32 v31, 0xffff0000, v108
	v_lshlrev_b32_e32 v84, 16, v109
	v_add_f32_e32 v31, v85, v31
	v_add_f32_e32 v85, v86, v84
	v_and_b32_e32 v84, 0xffff0000, v109
	v_add_f32_e32 v86, v87, v84
	v_cvt_pk_bf16_f32 v84, v29, v31
	v_cvt_pk_bf16_f32 v85, v85, v86
	global_store_dwordx2 v[144:145], v[84:85], off offset:96
	s_waitcnt vmcnt(7)
	v_lshlrev_b32_e32 v29, 16, v110
	v_add_f32_e32 v29, v80, v29
	v_and_b32_e32 v31, 0xffff0000, v110
	v_lshlrev_b32_e32 v80, 16, v111
	v_add_f32_e32 v31, v81, v31
	v_add_f32_e32 v81, v82, v80
	v_and_b32_e32 v80, 0xffff0000, v111
	v_add_f32_e32 v82, v83, v80
	v_cvt_pk_bf16_f32 v80, v29, v31
	v_cvt_pk_bf16_f32 v81, v81, v82
	global_store_dwordx2 v[144:145], v[80:81], off offset:128
	s_waitcnt vmcnt(7)
	v_lshlrev_b32_e32 v29, 16, v112
	v_add_f32_e32 v29, v76, v29
	v_and_b32_e32 v31, 0xffff0000, v112
	v_lshlrev_b32_e32 v76, 16, v113
	v_add_f32_e32 v31, v77, v31
	v_add_f32_e32 v77, v78, v76
	v_and_b32_e32 v76, 0xffff0000, v113
	v_add_f32_e32 v78, v79, v76
	v_cvt_pk_bf16_f32 v76, v29, v31
	v_cvt_pk_bf16_f32 v77, v77, v78
	global_store_dwordx2 v[144:145], v[76:77], off offset:160
	s_waitcnt vmcnt(7)
	v_lshlrev_b32_e32 v29, 16, v114
	v_add_f32_e32 v29, v72, v29
	v_and_b32_e32 v31, 0xffff0000, v114
	v_lshlrev_b32_e32 v72, 16, v115
	v_add_f32_e32 v31, v73, v31
	v_add_f32_e32 v73, v74, v72
	v_and_b32_e32 v72, 0xffff0000, v115
	v_add_f32_e32 v74, v75, v72
	v_cvt_pk_bf16_f32 v72, v29, v31
	v_cvt_pk_bf16_f32 v73, v73, v74
	global_store_dwordx2 v[144:145], v[72:73], off offset:192
	s_waitcnt vmcnt(7)
	v_lshlrev_b32_e32 v29, 16, v240
	v_add_f32_e32 v29, v68, v29
	v_and_b32_e32 v31, 0xffff0000, v240
	v_lshlrev_b32_e32 v68, 16, v241
	v_add_f32_e32 v31, v69, v31
	v_add_f32_e32 v69, v70, v68
	v_and_b32_e32 v68, 0xffff0000, v241
	v_add_f32_e32 v70, v71, v68
	v_cvt_pk_bf16_f32 v68, v29, v31
	v_cvt_pk_bf16_f32 v69, v69, v70
	global_store_dwordx2 v[144:145], v[68:69], off offset:224
	v_cmp_lt_f32_e32 vcc, 0, v117
	s_and_saveexec_b64 s[0:1], vcc
	s_cbranch_execz .LBB0_685
	v_mad_i64_i32 v[30:31], s[2:3], v156, s84, v[152:153]
	flat_load_dword v29, v[30:31] offset:4
	s_waitcnt vmcnt(0) lgkmcnt(0)
	v_div_scale_f32 v30, s[2:3], v117, v117, v29
	v_rcp_f32_e32 v31, v30
	v_div_scale_f32 v68, vcc, v29, v117, v29
	v_fma_f32 v69, -v30, v31, 1.0
	v_fmac_f32_e32 v31, v69, v31
	v_mul_f32_e32 v69, v68, v31
	v_fma_f32 v70, -v30, v69, v68
	v_fmac_f32_e32 v69, v70, v31
	v_fma_f32 v30, -v30, v69, v68
	v_div_fmas_f32 v30, v30, v31, v69
	v_div_fixup_f32 v30, v30, v117, v29
.LBB0_685:
	s_or_b64 exec, exec, s[0:1]
	v_lshl_add_u64 v[146:147], v[158:159], 0, v[162:163]
	global_load_dwordx2 v[68:69], v[146:147], off
	global_load_dwordx2 v[104:105], v[146:147], off offset:32
	global_load_dwordx2 v[106:107], v[146:147], off offset:64
	global_load_dwordx2 v[108:109], v[146:147], off offset:96
	global_load_dwordx2 v[110:111], v[146:147], off offset:128
	global_load_dwordx2 v[112:113], v[146:147], off offset:160
	global_load_dwordx2 v[114:115], v[146:147], off offset:192
	global_load_dwordx2 v[240:241], v[146:147], off offset:224
	v_pk_mul_f32 v[64:65], v[64:65], v[30:31] op_sel_hi:[1,0]
	v_pk_mul_f32 v[66:67], v[66:67], v[30:31] op_sel_hi:[1,0]
	s_waitcnt vmcnt(7)
	v_lshlrev_b32_e32 v29, 16, v68
	v_add_f32_e32 v29, v64, v29
	v_and_b32_e32 v31, 0xffff0000, v68
	v_lshlrev_b32_e32 v64, 16, v69
	v_add_f32_e32 v31, v65, v31
	v_add_f32_e32 v65, v66, v64
	v_and_b32_e32 v64, 0xffff0000, v69
	v_add_f32_e32 v66, v67, v64
	v_cvt_pk_bf16_f32 v64, v29, v31
	v_cvt_pk_bf16_f32 v65, v65, v66
	global_store_dwordx2 v[146:147], v[64:65], off
	v_pk_mul_f32 v[60:61], v[60:61], v[30:31] op_sel_hi:[1,0]
	v_pk_mul_f32 v[62:63], v[62:63], v[30:31] op_sel_hi:[1,0]
	s_waitcnt vmcnt(7)
	v_lshlrev_b32_e32 v29, 16, v104
	v_add_f32_e32 v29, v60, v29
	v_and_b32_e32 v31, 0xffff0000, v104
	v_lshlrev_b32_e32 v60, 16, v105
	v_add_f32_e32 v31, v61, v31
	v_add_f32_e32 v61, v62, v60
	v_and_b32_e32 v60, 0xffff0000, v105
	v_add_f32_e32 v62, v63, v60
	v_cvt_pk_bf16_f32 v60, v29, v31
	v_cvt_pk_bf16_f32 v61, v61, v62
	global_store_dwordx2 v[146:147], v[60:61], off offset:32
	v_pk_mul_f32 v[56:57], v[56:57], v[30:31] op_sel_hi:[1,0]
	v_pk_mul_f32 v[58:59], v[58:59], v[30:31] op_sel_hi:[1,0]
	s_waitcnt vmcnt(7)
	v_lshlrev_b32_e32 v29, 16, v106
	v_add_f32_e32 v29, v56, v29
	v_and_b32_e32 v31, 0xffff0000, v106
	v_lshlrev_b32_e32 v56, 16, v107
	v_add_f32_e32 v31, v57, v31
	v_add_f32_e32 v57, v58, v56
	v_and_b32_e32 v56, 0xffff0000, v107
	v_add_f32_e32 v58, v59, v56
	v_cvt_pk_bf16_f32 v56, v29, v31
	v_cvt_pk_bf16_f32 v57, v57, v58
	global_store_dwordx2 v[146:147], v[56:57], off offset:64
	v_pk_mul_f32 v[52:53], v[52:53], v[30:31] op_sel_hi:[1,0]
	v_pk_mul_f32 v[54:55], v[54:55], v[30:31] op_sel_hi:[1,0]
	s_waitcnt vmcnt(7)
	v_lshlrev_b32_e32 v29, 16, v108
	v_add_f32_e32 v29, v52, v29
	v_and_b32_e32 v31, 0xffff0000, v108
	v_lshlrev_b32_e32 v52, 16, v109
	v_add_f32_e32 v31, v53, v31
	v_add_f32_e32 v53, v54, v52
	v_and_b32_e32 v52, 0xffff0000, v109
	v_add_f32_e32 v54, v55, v52
	v_cvt_pk_bf16_f32 v52, v29, v31
	v_cvt_pk_bf16_f32 v53, v53, v54
	global_store_dwordx2 v[146:147], v[52:53], off offset:96
	v_pk_mul_f32 v[48:49], v[48:49], v[30:31] op_sel_hi:[1,0]
	v_pk_mul_f32 v[50:51], v[50:51], v[30:31] op_sel_hi:[1,0]
	s_waitcnt vmcnt(7)
	v_lshlrev_b32_e32 v29, 16, v110
	v_add_f32_e32 v29, v48, v29
	v_and_b32_e32 v31, 0xffff0000, v110
	v_lshlrev_b32_e32 v48, 16, v111
	v_add_f32_e32 v31, v49, v31
	v_add_f32_e32 v49, v50, v48
	v_and_b32_e32 v48, 0xffff0000, v111
	v_add_f32_e32 v50, v51, v48
	v_cvt_pk_bf16_f32 v48, v29, v31
	v_cvt_pk_bf16_f32 v49, v49, v50
	global_store_dwordx2 v[146:147], v[48:49], off offset:128
	v_pk_mul_f32 v[44:45], v[44:45], v[30:31] op_sel_hi:[1,0]
	v_pk_mul_f32 v[46:47], v[46:47], v[30:31] op_sel_hi:[1,0]
	s_waitcnt vmcnt(7)
	v_lshlrev_b32_e32 v29, 16, v112
	v_add_f32_e32 v29, v44, v29
	v_and_b32_e32 v31, 0xffff0000, v112
	v_lshlrev_b32_e32 v44, 16, v113
	v_add_f32_e32 v31, v45, v31
	v_add_f32_e32 v45, v46, v44
	v_and_b32_e32 v44, 0xffff0000, v113
	v_add_f32_e32 v46, v47, v44
	v_cvt_pk_bf16_f32 v44, v29, v31
	v_cvt_pk_bf16_f32 v45, v45, v46
	global_store_dwordx2 v[146:147], v[44:45], off offset:160
	v_pk_mul_f32 v[40:41], v[40:41], v[30:31] op_sel_hi:[1,0]
	v_pk_mul_f32 v[42:43], v[42:43], v[30:31] op_sel_hi:[1,0]
	s_waitcnt vmcnt(7)
	v_lshlrev_b32_e32 v29, 16, v114
	v_add_f32_e32 v29, v40, v29
	v_and_b32_e32 v31, 0xffff0000, v114
	v_lshlrev_b32_e32 v40, 16, v115
	v_add_f32_e32 v31, v41, v31
	v_add_f32_e32 v41, v42, v40
	v_and_b32_e32 v40, 0xffff0000, v115
	v_add_f32_e32 v42, v43, v40
	v_cvt_pk_bf16_f32 v40, v29, v31
	v_cvt_pk_bf16_f32 v41, v41, v42
	global_store_dwordx2 v[146:147], v[40:41], off offset:192
	v_pk_mul_f32 v[38:39], v[38:39], v[30:31] op_sel_hi:[1,0]
	v_pk_mul_f32 v[30:31], v[36:37], v[30:31] op_sel_hi:[1,0]
	s_waitcnt vmcnt(7)
	v_lshlrev_b32_e32 v29, 16, v240
	v_add_f32_e32 v29, v30, v29
	v_and_b32_e32 v30, 0xffff0000, v240
	v_add_f32_e32 v30, v31, v30
	v_lshlrev_b32_e32 v31, 16, v241
	v_add_f32_e32 v31, v38, v31
	v_and_b32_e32 v36, 0xffff0000, v241
	v_add_f32_e32 v36, v39, v36
	v_cvt_pk_bf16_f32 v30, v29, v30
	v_cvt_pk_bf16_f32 v31, v31, v36
	global_store_dwordx2 v[146:147], v[30:31], off offset:224
	s_addk_i32 s68, 0xfe01
	s_lshr_b32 s0, s68, 6
	s_cmp_gt_i32 s67, 7
	s_cselect_b32 s2, s0, 0
	s_sub_i32 s16, s67, s2
	v_cmp_ge_i32_e32 vcc, s16, v154
	s_and_saveexec_b64 s[0:1], vcc
	v_add_u32_e32 v29, s2, v154
	ds_write_b32 v188, v29
	s_or_b64 exec, exec, s[0:1]
	s_cmp_eq_u32 s16, -1
	s_waitcnt lgkmcnt(0)
	s_barrier
	s_cbranch_scc1 .LBB0_711
	v_mov_b32_e32 v29, s50
	ds_read_b32 v29, v29
	s_lshl_b32 s0, s26, 1
	s_add_u32 s0, s64, s0
	s_addc_u32 s1, s65, 0
	s_lshl_b32 s2, s27, 1
	s_waitcnt lgkmcnt(0)
	v_lshlrev_b32_e32 v36, 6, v29
	s_add_u32 s10, s47, s2
	s_mov_b32 s2, 0x60000
	v_ashrrev_i32_e32 v37, 31, v36
	v_add_u32_e32 v53, 0x200, v154
	s_addc_u32 s11, s46, 0
	v_mul_hi_i32 v31, v29, s2
	v_mul_lo_u32 v30, v29, s2
	v_lshlrev_b64 v[36:37], 1, v[36:37]
	v_lshlrev_b32_e32 v29, 3, v154
	v_lshrrev_b32_e32 v52, 4, v154
	s_movk_i32 s2, 0xc00
	v_lshrrev_b32_e32 v54, 4, v53
	v_lshl_add_u64 v[48:49], s[10:11], 0, v[36:37]
	v_and_b32_e32 v40, 0x78, v29
	v_mul_lo_u32 v36, v52, s2
	v_mul_lo_u32 v41, v54, s2
	v_lshl_add_u64 v[30:31], s[0:1], 0, v[30:31]
	v_or_b32_e32 v158, v36, v40
	v_mov_b32_e32 v159, v28
	v_or_b32_e32 v162, v41, v40
	v_mov_b32_e32 v163, v28
	v_lshl_add_u64 v[36:37], v[158:159], 1, v[30:31]
	v_lshl_add_u64 v[30:31], v[162:163], 1, v[30:31]
	global_load_dwordx4 v[36:39], v[36:37], off
	v_and_b32_e32 v29, 56, v29
	global_load_dwordx4 v[40:43], v[30:31], off
	v_lshlrev_b32_e32 v30, 10, v154
	s_movk_i32 s2, 0xe000
	v_and_or_b32 v164, v30, s2, v29
	v_mov_b32_e32 v165, v28
	v_lshl_add_u64 v[30:31], v[164:165], 1, v[48:49]
	global_load_dwordx4 v[44:47], v[30:31], off
	v_lshlrev_b32_e32 v30, 10, v53
	v_and_or_b32 v166, v30, s2, v29
	v_mov_b32_e32 v167, v28
	v_lshl_add_u64 v[30:31], v[166:167], 1, v[48:49]
	global_load_dwordx4 v[48:51], v[30:31], off
	v_lshlrev_b32_e32 v30, 4, v154
	v_and_b32_e32 v29, 0xf0, v30
	v_add_u32_e32 v31, s54, v29
	v_mul_lo_u32 v157, v52, s83
	v_add_u32_e32 v161, v31, v157
	v_mul_lo_u32 v168, v54, s83
	v_and_b32_e32 v30, 0x70, v30
	v_add_u32_e32 v169, v31, v168
	v_add_u32_e32 v31, s79, v30
	s_cmp_lt_i32 s16, 0
	s_waitcnt vmcnt(0)
	ds_write_b128 v161, v[36:39]
	v_lshrrev_b32_e32 v36, 3, v154
	v_mul_lo_u32 v154, v36, s88
	v_lshrrev_b32_e32 v36, 3, v53
	v_mul_lo_u32 v171, v36, s88
	v_add_u32_e32 v170, v31, v154
	v_add_u32_e32 v172, v31, v171
	ds_write_b128 v169, v[40:43]
	ds_write_b128 v170, v[44:47]
	ds_write_b128 v172, v[48:51]
	s_waitcnt lgkmcnt(0)
	s_barrier
	s_cbranch_scc1 .LBB0_712
	v_ashrrev_i32_e32 v39, 4, v155
	v_and_b32_e32 v31, 15, v155
	v_and_b32_e32 v36, -16, v155
	v_lshlrev_b32_e32 v155, 2, v39
	v_lshlrev_b32_e32 v39, 3, v39
	v_add_u32_e32 v37, s54, v36
	v_mul_u32_u24_e32 v38, 0x110, v31
	v_add_u32_e32 v40, s79, v39
	v_mul_u32_u24_e32 v41, 0x90, v31
	v_add_u32_e32 v173, 0, v30
	v_add_u32_e32 v36, 0, v36
	v_add_u32_e32 v39, 0, v39
	v_mov_b32_e32 v30, v28
	v_mov_b32_e32 v31, v28
	v_add_u32_e32 v174, 0, v29
	v_mov_b32_e32 v29, v28
	v_add_u32_e32 v176, v37, v38
	v_add_u32_e32 v177, v40, v41
	v_add_u32_e32 v178, v36, v38
	v_add_u32_e32 v179, v39, v41
	v_mov_b64_e32 v[38:39], v[30:31]
	v_mov_b64_e32 v[42:43], v[30:31]
	v_mov_b64_e32 v[46:47], v[30:31]
	v_mov_b64_e32 v[50:51], v[30:31]
	v_mov_b64_e32 v[54:55], v[30:31]
	v_mov_b64_e32 v[58:59], v[30:31]
	v_mov_b64_e32 v[62:63], v[30:31]
	v_mov_b64_e32 v[66:67], v[30:31]
	v_mov_b64_e32 v[70:71], v[30:31]
	v_mov_b64_e32 v[74:75], v[30:31]
	v_mov_b64_e32 v[78:79], v[30:31]
	v_mov_b64_e32 v[82:83], v[30:31]
	v_mov_b64_e32 v[86:87], v[30:31]
	v_mov_b64_e32 v[90:91], v[30:31]
	v_mov_b64_e32 v[94:95], v[30:31]
	v_mov_b64_e32 v[98:99], v[30:31]
	v_add_u32_e32 v175, -16, v160
	s_add_i32 s17, 0, 0x14848
	s_mov_b32 s18, 0
	v_mov_b32_e32 v180, 0
	v_mov_b32_e32 v182, 0xf149f2ca
	v_mov_b64_e32 v[36:37], v[28:29]
	v_mov_b64_e32 v[40:41], v[28:29]
	v_mov_b64_e32 v[44:45], v[28:29]
	v_mov_b64_e32 v[48:49], v[28:29]
	v_mov_b64_e32 v[52:53], v[28:29]
	v_mov_b64_e32 v[56:57], v[28:29]
	v_mov_b64_e32 v[60:61], v[28:29]
	v_mov_b64_e32 v[64:65], v[28:29]
	v_mov_b64_e32 v[68:69], v[28:29]
	v_mov_b64_e32 v[72:73], v[28:29]
	v_mov_b64_e32 v[76:77], v[28:29]
	v_mov_b64_e32 v[80:81], v[28:29]
	v_mov_b64_e32 v[84:85], v[28:29]
	v_mov_b64_e32 v[88:89], v[28:29]
	v_mov_b64_e32 v[92:93], v[28:29]
	v_mov_b64_e32 v[96:97], v[28:29]
	v_mov_b32_e32 v29, 0xf149f2ca
	v_mov_b32_e32 v181, 0
	s_branch .LBB0_691

.LBB0_715:
	s_or_b64 exec, exec, s[0:1]
	global_load_dwordx2 v[4:5], v[144:145], off
	global_load_dwordx2 v[104:105], v[144:145], off offset:32
	global_load_dwordx2 v[106:107], v[144:145], off offset:64
	global_load_dwordx2 v[108:109], v[144:145], off offset:96
	global_load_dwordx2 v[110:111], v[144:145], off offset:128
	global_load_dwordx2 v[112:113], v[144:145], off offset:160
	global_load_dwordx2 v[114:115], v[144:145], off offset:192
	global_load_dwordx2 v[240:241], v[144:145], off offset:224
	v_pk_mul_f32 v[6:7], v[98:99], v[2:3] op_sel_hi:[1,0]
	v_pk_mul_f32 v[8:9], v[96:97], v[2:3] op_sel_hi:[1,0]
	s_waitcnt vmcnt(7)
	v_lshlrev_b32_e32 v1, 16, v4
	v_and_b32_e32 v3, 0xffff0000, v4
	v_lshlrev_b32_e32 v4, 16, v5
	v_add_f32_e32 v6, v6, v4
	v_and_b32_e32 v4, 0xffff0000, v5
	v_add_f32_e32 v5, v7, v4
	v_add_f32_e32 v1, v8, v1
	v_add_f32_e32 v3, v9, v3
	v_cvt_pk_bf16_f32 v4, v1, v3
	v_cvt_pk_bf16_f32 v5, v6, v5
	global_store_dwordx2 v[144:145], v[4:5], off
	v_pk_mul_f32 v[6:7], v[94:95], v[2:3] op_sel_hi:[1,0]
	v_pk_mul_f32 v[8:9], v[92:93], v[2:3] op_sel_hi:[1,0]
	s_waitcnt vmcnt(7)
	v_lshlrev_b32_e32 v1, 16, v104
	v_and_b32_e32 v3, 0xffff0000, v104
	v_lshlrev_b32_e32 v4, 16, v105
	v_add_f32_e32 v6, v6, v4
	v_and_b32_e32 v4, 0xffff0000, v105
	v_add_f32_e32 v5, v7, v4
	v_add_f32_e32 v1, v8, v1
	v_add_f32_e32 v3, v9, v3
	v_cvt_pk_bf16_f32 v4, v1, v3
	v_cvt_pk_bf16_f32 v5, v6, v5
	global_store_dwordx2 v[144:145], v[4:5], off offset:32
	v_pk_mul_f32 v[6:7], v[90:91], v[2:3] op_sel_hi:[1,0]
	v_pk_mul_f32 v[8:9], v[88:89], v[2:3] op_sel_hi:[1,0]
	s_waitcnt vmcnt(7)
	v_lshlrev_b32_e32 v1, 16, v106
	v_and_b32_e32 v3, 0xffff0000, v106
	v_lshlrev_b32_e32 v4, 16, v107
	v_add_f32_e32 v6, v6, v4
	v_and_b32_e32 v4, 0xffff0000, v107
	v_add_f32_e32 v5, v7, v4
	v_add_f32_e32 v1, v8, v1
	v_add_f32_e32 v3, v9, v3
	v_cvt_pk_bf16_f32 v4, v1, v3
	v_cvt_pk_bf16_f32 v5, v6, v5
	global_store_dwordx2 v[144:145], v[4:5], off offset:64
	v_pk_mul_f32 v[6:7], v[86:87], v[2:3] op_sel_hi:[1,0]
	v_pk_mul_f32 v[8:9], v[84:85], v[2:3] op_sel_hi:[1,0]
	s_waitcnt vmcnt(7)
	v_lshlrev_b32_e32 v1, 16, v108
	v_and_b32_e32 v3, 0xffff0000, v108
	v_lshlrev_b32_e32 v4, 16, v109
	v_add_f32_e32 v6, v6, v4
	v_and_b32_e32 v4, 0xffff0000, v109
	v_add_f32_e32 v5, v7, v4
	v_add_f32_e32 v1, v8, v1
	v_add_f32_e32 v3, v9, v3
	v_cvt_pk_bf16_f32 v4, v1, v3
	v_cvt_pk_bf16_f32 v5, v6, v5
	global_store_dwordx2 v[144:145], v[4:5], off offset:96
	v_pk_mul_f32 v[6:7], v[82:83], v[2:3] op_sel_hi:[1,0]
	v_pk_mul_f32 v[8:9], v[80:81], v[2:3] op_sel_hi:[1,0]
	s_waitcnt vmcnt(7)
	v_lshlrev_b32_e32 v1, 16, v110
	v_and_b32_e32 v3, 0xffff0000, v110
	v_lshlrev_b32_e32 v4, 16, v111
	v_add_f32_e32 v6, v6, v4
	v_and_b32_e32 v4, 0xffff0000, v111
	v_add_f32_e32 v5, v7, v4
	v_add_f32_e32 v1, v8, v1
	v_add_f32_e32 v3, v9, v3
	v_cvt_pk_bf16_f32 v4, v1, v3
	v_cvt_pk_bf16_f32 v5, v6, v5
	global_store_dwordx2 v[144:145], v[4:5], off offset:128
	v_pk_mul_f32 v[6:7], v[78:79], v[2:3] op_sel_hi:[1,0]
	v_pk_mul_f32 v[8:9], v[76:77], v[2:3] op_sel_hi:[1,0]
	s_waitcnt vmcnt(7)
	v_lshlrev_b32_e32 v1, 16, v112
	v_and_b32_e32 v3, 0xffff0000, v112
	v_lshlrev_b32_e32 v4, 16, v113
	v_add_f32_e32 v6, v6, v4
	v_and_b32_e32 v4, 0xffff0000, v113
	v_add_f32_e32 v5, v7, v4
	v_add_f32_e32 v1, v8, v1
	v_add_f32_e32 v3, v9, v3
	v_cvt_pk_bf16_f32 v4, v1, v3
	v_cvt_pk_bf16_f32 v5, v6, v5
	global_store_dwordx2 v[144:145], v[4:5], off offset:160
	v_pk_mul_f32 v[6:7], v[74:75], v[2:3] op_sel_hi:[1,0]
	v_pk_mul_f32 v[8:9], v[72:73], v[2:3] op_sel_hi:[1,0]
	s_waitcnt vmcnt(7)
	v_lshlrev_b32_e32 v1, 16, v114
	v_and_b32_e32 v3, 0xffff0000, v114
	v_lshlrev_b32_e32 v4, 16, v115
	v_add_f32_e32 v6, v6, v4
	v_and_b32_e32 v4, 0xffff0000, v115
	v_add_f32_e32 v5, v7, v4
	v_add_f32_e32 v1, v8, v1
	v_add_f32_e32 v3, v9, v3
	v_cvt_pk_bf16_f32 v4, v1, v3
	v_cvt_pk_bf16_f32 v5, v6, v5
	global_store_dwordx2 v[144:145], v[4:5], off offset:192
	v_pk_mul_f32 v[6:7], v[70:71], v[2:3] op_sel_hi:[1,0]
	v_pk_mul_f32 v[2:3], v[68:69], v[2:3] op_sel_hi:[1,0]
	s_waitcnt vmcnt(7)
	v_lshlrev_b32_e32 v1, 16, v240
	v_add_f32_e32 v1, v2, v1
	v_and_b32_e32 v2, 0xffff0000, v240
	v_add_f32_e32 v2, v3, v2
	v_lshlrev_b32_e32 v3, 16, v241
	v_add_f32_e32 v3, v6, v3
	v_and_b32_e32 v4, 0xffff0000, v241
	v_add_f32_e32 v4, v7, v4
	v_cvt_pk_bf16_f32 v2, v1, v2
	v_cvt_pk_bf16_f32 v3, v3, v4
	global_store_dwordx2 v[144:145], v[2:3], off offset:224
	v_cmp_lt_f32_e32 vcc, 0, v180
	s_and_saveexec_b64 s[0:1], vcc
	s_cbranch_execz .LBB0_528
	v_mad_i64_i32 v[0:1], s[2:3], v156, s84, v[152:153]
	flat_load_dword v0, v[0:1] offset:8
	s_waitcnt vmcnt(0) lgkmcnt(0)
	v_div_scale_f32 v1, s[2:3], v180, v180, v0
	v_rcp_f32_e32 v2, v1
	v_div_scale_f32 v3, vcc, v0, v180, v0
	v_fma_f32 v4, -v1, v2, 1.0
	v_fmac_f32_e32 v2, v4, v2
	v_mul_f32_e32 v4, v3, v2
	v_fma_f32 v5, -v1, v4, v3
	v_fmac_f32_e32 v4, v5, v2
	v_fma_f32 v1, -v1, v4, v3
	v_div_fmas_f32 v1, v1, v2, v4
	v_div_fixup_f32 v0, v1, v180, v0
	s_branch .LBB0_528
